# widen narrow stores: P0 normalised-stream rows stored as 16-byte pieces (DPP lane pairing) instead of 8-byte pieces
# speedup vs baseline: 1.0070x; 1.0070x over previous
.LBB0_42:
	v_lshl_add_u64 v[10:11], s[24:25], 0, v[2:3]
	v_lshl_add_u64 v[12:13], s[20:21], 0, v[2:3]
	global_load_dwordx4 v[22:25], v[10:11], off nt
	global_load_dwordx4 v[26:29], v[12:13], off nt
	global_load_dwordx4 v[30:33], v[10:11], off offset:1024 nt
	global_load_dwordx4 v[34:37], v[12:13], off offset:1024 nt
	global_load_dwordx4 v[38:41], v[10:11], off offset:2048 nt
	global_load_dwordx4 v[42:45], v[12:13], off offset:2048 nt
	global_load_dwordx4 v[46:49], v[10:11], off offset:3072 nt
	s_nop 0
	global_load_dwordx4 v[10:13], v[12:13], off offset:3072 nt
	s_add_i32 s12, s12, s14
	s_add_u32 s20, s20, s22
	s_addc_u32 s21, s21, s23
	s_add_u32 s24, s24, s22
	v_lshl_add_u64 v[8:9], v[4:5], 0, s[16:17]
	s_addc_u32 s25, s25, s23
	v_lshl_add_u64 v[6:7], v[4:5], 0, s[26:27]
	v_lshl_add_u64 v[4:5], v[4:5], 0, s[18:19]
	s_cmpk_gt_i32 s12, 0x7fff
	s_waitcnt vmcnt(7)
	v_mul_f32_e32 v50, v23, v23
	v_mul_f32_e32 v51, v25, v25
	s_waitcnt vmcnt(6)
	v_mul_f32_e32 v52, v27, v27
	v_mul_f32_e32 v53, v29, v29
	s_waitcnt vmcnt(5)
	v_mul_f32_e32 v54, v31, v31
	v_mul_f32_e32 v55, v33, v33
	s_waitcnt vmcnt(4)
	v_mul_f32_e32 v56, v35, v35
	v_mul_f32_e32 v57, v37, v37
	s_waitcnt vmcnt(3)
	v_mul_f32_e32 v58, v39, v39
	v_mul_f32_e32 v59, v41, v41
	v_fmac_f32_e32 v50, v22, v22
	v_fmac_f32_e32 v51, v24, v24
	v_fmac_f32_e32 v52, v26, v26
	v_fmac_f32_e32 v53, v28, v28
	v_fmac_f32_e32 v54, v30, v30
	v_fmac_f32_e32 v55, v32, v32
	s_waitcnt vmcnt(2)
	v_mul_f32_e32 v60, v43, v43
	v_mul_f32_e32 v61, v45, v45
	s_waitcnt vmcnt(1)
	v_mul_f32_e32 v62, v47, v47
	v_mul_f32_e32 v63, v49, v49
	v_fmac_f32_e32 v56, v34, v34
	v_fmac_f32_e32 v57, v36, v36
	v_fmac_f32_e32 v58, v38, v38
	v_fmac_f32_e32 v59, v40, v40
	v_add_f32_e32 v50, v50, v51
	v_add_f32_e32 v51, v52, v53
	v_add_f32_e32 v52, v54, v55
	s_waitcnt vmcnt(0)
	v_mul_f32_e32 v64, v11, v11
	v_mul_f32_e32 v65, v13, v13
	v_fmac_f32_e32 v60, v42, v42
	v_fmac_f32_e32 v61, v44, v44
	v_fmac_f32_e32 v62, v46, v46
	v_fmac_f32_e32 v63, v48, v48
	v_add_f32_e32 v53, v56, v57
	v_add_f32_e32 v54, v58, v59
	v_add_f32_e32 v50, v50, v52
	v_fmac_f32_e32 v64, v10, v10
	v_fmac_f32_e32 v65, v12, v12
	v_add_f32_e32 v55, v60, v61
	v_add_f32_e32 v56, v62, v63
	v_add_f32_e32 v51, v51, v53
	v_add_f32_e32 v50, v50, v54
	v_add_f32_e32 v57, v64, v65
	v_add_f32_e32 v51, v51, v55
	v_add_f32_e32 v50, v50, v56
	v_add_f32_e32 v51, v51, v57
	ds_bpermute_b32 v52, v15, v50
	ds_bpermute_b32 v53, v15, v51
	s_waitcnt lgkmcnt(1)
	v_add_f32_e32 v50, v50, v52
	s_waitcnt lgkmcnt(0)
	v_add_f32_e32 v51, v51, v53
	ds_bpermute_b32 v52, v16, v50
	ds_bpermute_b32 v53, v16, v51
	s_waitcnt lgkmcnt(1)
	v_add_f32_e32 v50, v50, v52
	s_waitcnt lgkmcnt(0)
	v_add_f32_e32 v51, v51, v53
	ds_bpermute_b32 v52, v17, v50
	ds_bpermute_b32 v53, v17, v51
	s_waitcnt lgkmcnt(1)
	v_add_f32_e32 v50, v50, v52
	s_waitcnt lgkmcnt(0)
	v_add_f32_e32 v51, v51, v53
	ds_bpermute_b32 v52, v18, v50
	ds_bpermute_b32 v53, v18, v51
	s_waitcnt lgkmcnt(1)
	v_add_f32_e32 v50, v50, v52
	s_waitcnt lgkmcnt(0)
	v_add_f32_e32 v51, v51, v53
	ds_bpermute_b32 v52, v19, v50
	ds_bpermute_b32 v53, v19, v51
	s_waitcnt lgkmcnt(1)
	v_add_f32_e32 v50, v50, v52
	s_waitcnt lgkmcnt(0)
	v_add_f32_e32 v51, v51, v53
	ds_bpermute_b32 v52, v20, v50
	ds_bpermute_b32 v53, v20, v51
	s_waitcnt lgkmcnt(1)
	v_add_f32_e32 v50, v50, v52
	s_waitcnt lgkmcnt(0)
	v_add_f32_e32 v51, v51, v53
	v_fmamk_f32 v50, v50, 0x3a800000, v1
	v_fmamk_f32 v51, v51, 0x3a800000, v1
	v_mul_f32_e32 v52, 0x4f800000, v50
	v_cmp_gt_f32_e64 s[0:1], s13, v50
	v_mul_f32_e32 v53, 0x4f800000, v51
	v_cmp_gt_f32_e32 vcc, s13, v51
	v_cndmask_b32_e64 v50, v50, v52, s[0:1]
	v_sqrt_f32_e32 v52, v50
	v_cndmask_b32_e32 v51, v51, v53, vcc
	v_sqrt_f32_e32 v53, v51
	v_add_u32_e32 v54, -1, v52
	v_add_u32_e32 v55, 1, v52
	v_add_u32_e32 v56, -1, v53
	v_fma_f32 v58, -v54, v52, v50
	v_add_u32_e32 v57, 1, v53
	v_fma_f32 v59, -v55, v52, v50
	v_fma_f32 v60, -v56, v53, v51
	v_cmp_ge_f32_e64 s[4:5], 0, v58
	v_fma_f32 v61, -v57, v53, v51
	v_cmp_lt_f32_e64 s[6:7], 0, v59
	v_cndmask_b32_e64 v52, v52, v54, s[4:5]
	v_cmp_ge_f32_e64 s[4:5], 0, v60
	v_cndmask_b32_e64 v52, v52, v55, s[6:7]
	v_mul_f32_e32 v54, 0x37800000, v52
	v_cndmask_b32_e64 v53, v53, v56, s[4:5]
	v_cmp_lt_f32_e64 s[4:5], 0, v61
	v_cndmask_b32_e64 v52, v52, v54, s[0:1]
	v_cmp_class_f32_e64 s[0:1], v50, v21
	v_cndmask_b32_e64 v53, v53, v57, s[4:5]
	v_mul_f32_e32 v55, 0x37800000, v53
	v_cndmask_b32_e32 v53, v53, v55, vcc
	v_cmp_class_f32_e32 vcc, v51, v21
	v_cndmask_b32_e64 v50, v52, v50, s[0:1]
	v_div_scale_f32 v52, s[0:1], v50, v50, 1.0
	v_cndmask_b32_e32 v51, v53, v51, vcc
	v_div_scale_f32 v54, s[0:1], v51, v51, 1.0
	v_rcp_f32_e32 v56, v52
	v_rcp_f32_e32 v57, v54
	v_div_scale_f32 v53, vcc, 1.0, v50, 1.0
	v_fma_f32 v58, -v52, v56, 1.0
	v_fma_f32 v59, -v54, v57, 1.0
	v_fmac_f32_e32 v56, v58, v56
	v_div_scale_f32 v55, s[0:1], 1.0, v51, 1.0
	v_fmac_f32_e32 v57, v59, v57
	v_mul_f32_e32 v58, v53, v56
	v_mul_f32_e32 v59, v55, v57
	v_fma_f32 v60, -v52, v58, v53
	v_fma_f32 v61, -v54, v59, v55
	v_fmac_f32_e32 v58, v60, v56
	v_fmac_f32_e32 v59, v61, v57
	v_fma_f32 v52, -v52, v58, v53
	v_fma_f32 v53, -v54, v59, v55
	v_div_fmas_f32 v52, v52, v56, v58
	s_mov_b64 vcc, s[0:1]
	v_div_fixup_f32 v50, v52, v50, 1.0
	v_div_fmas_f32 v52, v53, v57, v59
	v_div_fixup_f32 v51, v52, v51, 1.0
	v_mul_f32_e32 v22, v50, v22
	v_mul_f32_e32 v23, v50, v23
	v_mul_f32_e32 v24, v50, v24
	v_mul_f32_e32 v25, v50, v25
	v_mul_f32_e32 v30, v50, v30
	v_mul_f32_e32 v31, v50, v31
	v_mul_f32_e32 v32, v50, v32
	v_mul_f32_e32 v33, v50, v33
	v_mul_f32_e32 v38, v50, v38
	v_mul_f32_e32 v39, v50, v39
	v_mul_f32_e32 v40, v50, v40
	v_mul_f32_e32 v41, v50, v41
	v_mul_f32_e32 v46, v50, v46
	v_mul_f32_e32 v47, v50, v47
	v_mul_f32_e32 v48, v50, v48
	v_mul_f32_e32 v49, v50, v49
	v_bfe_u32 v50, v22, 16, 1
	v_bfe_u32 v52, v23, 16, 1
	v_bfe_u32 v53, v24, 16, 1
	v_mul_f32_e32 v26, v51, v26
	v_mul_f32_e32 v28, v51, v28
	v_bfe_u32 v54, v25, 16, 1
	v_mul_f32_e32 v27, v51, v27
	v_mul_f32_e32 v29, v51, v29
	v_bfe_u32 v55, v30, 16, 1
	v_bfe_u32 v56, v31, 16, 1
	v_bfe_u32 v57, v32, 16, 1
	v_bfe_u32 v58, v33, 16, 1
	v_mul_f32_e32 v34, v51, v34
	v_mul_f32_e32 v36, v51, v36
	v_bfe_u32 v59, v38, 16, 1
	v_bfe_u32 v60, v39, 16, 1
	v_bfe_u32 v61, v40, 16, 1
	v_bfe_u32 v62, v41, 16, 1
	v_mul_f32_e32 v42, v51, v42
	v_mul_f32_e32 v44, v51, v44
	v_bfe_u32 v63, v46, 16, 1
	v_bfe_u32 v64, v47, 16, 1
	v_bfe_u32 v65, v48, 16, 1
	v_mul_f32_e32 v10, v51, v10
	v_mul_f32_e32 v11, v51, v11
	v_mul_f32_e32 v12, v51, v12
	v_add3_u32 v22, v22, v50, s29
	v_add3_u32 v23, v23, v52, s29
	v_add3_u32 v24, v24, v53, s29
	v_bfe_u32 v50, v26, 16, 1
	v_bfe_u32 v52, v28, 16, 1
	v_mul_f32_e32 v35, v51, v35
	v_mul_f32_e32 v37, v51, v37
	v_mul_f32_e32 v43, v51, v43
	v_mul_f32_e32 v45, v51, v45
	v_bfe_u32 v66, v49, 16, 1
	v_mul_f32_e32 v13, v51, v13
	v_add3_u32 v25, v25, v54, s29
	v_bfe_u32 v51, v27, 16, 1
	v_bfe_u32 v53, v29, 16, 1
	v_add3_u32 v30, v30, v55, s29
	v_add3_u32 v31, v31, v56, s29
	v_add3_u32 v32, v32, v57, s29
	v_add3_u32 v33, v33, v58, s29
	v_bfe_u32 v54, v34, 16, 1
	v_bfe_u32 v56, v36, 16, 1
	v_add3_u32 v38, v38, v59, s29
	v_add3_u32 v39, v39, v60, s29
	v_add3_u32 v40, v40, v61, s29
	v_add3_u32 v41, v41, v62, s29
	v_bfe_u32 v58, v42, 16, 1
	v_bfe_u32 v60, v44, 16, 1
	v_add3_u32 v46, v46, v63, s29
	v_add3_u32 v47, v47, v64, s29
	v_add3_u32 v48, v48, v65, s29
	v_bfe_u32 v62, v10, 16, 1
	v_bfe_u32 v63, v11, 16, 1
	v_bfe_u32 v64, v12, 16, 1
	v_lshrrev_b32_e32 v22, 16, v22
	v_lshrrev_b32_e32 v24, 16, v24
	v_add3_u32 v26, v26, v50, s29
	v_add3_u32 v28, v28, v52, s29
	v_bfe_u32 v55, v35, 16, 1
	v_bfe_u32 v57, v37, 16, 1
	v_bfe_u32 v59, v43, 16, 1
	v_bfe_u32 v61, v45, 16, 1
	v_add3_u32 v49, v49, v66, s29
	v_bfe_u32 v65, v13, 16, 1
	v_add3_u32 v27, v27, v51, s29
	v_add3_u32 v29, v29, v53, s29
	v_lshrrev_b32_e32 v30, 16, v30
	v_lshrrev_b32_e32 v32, 16, v32
	v_add3_u32 v34, v34, v54, s29
	v_add3_u32 v36, v36, v56, s29
	v_lshrrev_b32_e32 v38, 16, v38
	v_lshrrev_b32_e32 v40, 16, v40
	v_add3_u32 v42, v42, v58, s29
	v_add3_u32 v44, v44, v60, s29
	v_lshrrev_b32_e32 v46, 16, v46
	v_lshrrev_b32_e32 v48, 16, v48
	v_add3_u32 v50, v10, v62, s29
	v_add3_u32 v51, v11, v63, s29
	v_add3_u32 v52, v12, v64, s29
	v_and_or_b32 v10, v23, s15, v22
	v_and_or_b32 v11, v25, s15, v24
	v_lshrrev_b32_e32 v26, 16, v26
	v_lshrrev_b32_e32 v28, 16, v28
	v_add3_u32 v35, v35, v55, s29
	v_add3_u32 v37, v37, v57, s29
	v_add3_u32 v43, v43, v59, s29
	v_add3_u32 v45, v45, v61, s29
	v_add3_u32 v53, v13, v65, s29
	v_and_or_b32 v12, v31, s15, v30
	v_and_or_b32 v13, v33, s15, v32
	v_lshrrev_b32_e32 v30, 16, v34
	v_lshrrev_b32_e32 v31, 16, v36
	v_and_or_b32 v22, v39, s15, v38
	v_and_or_b32 v23, v41, s15, v40
	v_lshrrev_b32_e32 v32, 16, v42
	v_lshrrev_b32_e32 v33, 16, v44
	v_and_or_b32 v24, v47, s15, v46
	v_and_or_b32 v25, v49, s15, v48
	v_lshrrev_b32_e32 v34, 16, v50
	v_lshrrev_b32_e32 v36, 16, v52
	s_mov_b32 vcc_lo, 0xaaaaaaaa
	s_mov_b32 vcc_hi, 0xaaaaaaaa
	v_mov_b32_e32 v119, 0
	v_mov_b32_e32 v117, 0x1f8
	v_cndmask_b32_e32 v118, v119, v117, vcc
	v_lshl_add_u64 v[120:121], v[8:9], 0, v[118:119]
	v_lshl_add_u64 v[122:123], v[6:7], 0, v[118:119]
	s_nop 1
	v_mov_b32_dpp v124, v10 quad_perm:[1,0,3,2] row_mask:0xf bank_mask:0xf
	v_mov_b32_dpp v125, v11 quad_perm:[1,0,3,2] row_mask:0xf bank_mask:0xf
	v_mov_b32_dpp v126, v12 quad_perm:[1,0,3,2] row_mask:0xf bank_mask:0xf
	v_mov_b32_dpp v127, v13 quad_perm:[1,0,3,2] row_mask:0xf bank_mask:0xf
	v_cndmask_b32_e32 v100, v10, v126, vcc
	v_cndmask_b32_e32 v101, v11, v127, vcc
	v_cndmask_b32_e32 v102, v124, v12, vcc
	v_cndmask_b32_e32 v103, v125, v13, vcc
	global_store_dwordx4 v[120:121], v[100:103], off offset:-1024
	s_nop 1
	v_mov_b32_dpp v124, v22 quad_perm:[1,0,3,2] row_mask:0xf bank_mask:0xf
	v_mov_b32_dpp v125, v23 quad_perm:[1,0,3,2] row_mask:0xf bank_mask:0xf
	v_mov_b32_dpp v126, v24 quad_perm:[1,0,3,2] row_mask:0xf bank_mask:0xf
	v_mov_b32_dpp v127, v25 quad_perm:[1,0,3,2] row_mask:0xf bank_mask:0xf
	v_cndmask_b32_e32 v104, v22, v126, vcc
	v_cndmask_b32_e32 v105, v23, v127, vcc
	v_cndmask_b32_e32 v106, v124, v24, vcc
	v_cndmask_b32_e32 v107, v125, v25, vcc
	global_store_dwordx4 v[120:121], v[104:107], off
	v_and_or_b32 v10, v27, s15, v26
	v_and_or_b32 v11, v29, s15, v28
	v_and_or_b32 v12, v35, s15, v30
	v_and_or_b32 v13, v37, s15, v31
	v_and_or_b32 v22, v43, s15, v32
	v_and_or_b32 v23, v45, s15, v33
	v_and_or_b32 v8, v51, s15, v34
	v_and_or_b32 v9, v53, s15, v36
	s_nop 1
	v_mov_b32_dpp v124, v10 quad_perm:[1,0,3,2] row_mask:0xf bank_mask:0xf
	v_mov_b32_dpp v125, v11 quad_perm:[1,0,3,2] row_mask:0xf bank_mask:0xf
	v_mov_b32_dpp v126, v12 quad_perm:[1,0,3,2] row_mask:0xf bank_mask:0xf
	v_mov_b32_dpp v127, v13 quad_perm:[1,0,3,2] row_mask:0xf bank_mask:0xf
	v_cndmask_b32_e32 v108, v10, v126, vcc
	v_cndmask_b32_e32 v109, v11, v127, vcc
	v_cndmask_b32_e32 v110, v124, v12, vcc
	v_cndmask_b32_e32 v111, v125, v13, vcc
	global_store_dwordx4 v[122:123], v[108:111], off offset:-1024
	s_nop 1
	v_mov_b32_dpp v124, v22 quad_perm:[1,0,3,2] row_mask:0xf bank_mask:0xf
	v_mov_b32_dpp v125, v23 quad_perm:[1,0,3,2] row_mask:0xf bank_mask:0xf
	v_mov_b32_dpp v126, v8 quad_perm:[1,0,3,2] row_mask:0xf bank_mask:0xf
	v_mov_b32_dpp v127, v9 quad_perm:[1,0,3,2] row_mask:0xf bank_mask:0xf
	v_cndmask_b32_e32 v112, v22, v126, vcc
	v_cndmask_b32_e32 v113, v23, v127, vcc
	v_cndmask_b32_e32 v114, v124, v8, vcc
	v_cndmask_b32_e32 v115, v125, v9, vcc
	global_store_dwordx4 v[122:123], v[112:115], off
	s_cbranch_scc0 .LBB0_42
